# v24 with LayerNorm unrolled over 8 rows and 3 rotating row buffers (2-3 rows in flight per wave)
# speedup vs baseline: 1.0144x; 1.0088x over previous
; #define TIDX tid_()
; DEVI int wave_() { return __builtin_amdgcn_readfirstlane(tid_() >> 6); }
; DEVI unsigned pk_bf16(float lo, float hi) { const bf16x2n r = __builtin_convertvector((f32x2v){lo, hi}, bf16x2n); return __builtin_bit_cast(unsigned, r); }
; DEVI void phase_ln(const Params& p, int l, int which, bool last) {
;     float* hbuf = (float*)(p.ws + OFF_H);
;     bf16_t* hb = (bf16_t*)(p.ws + OFF_HB);
;     float* dst = last ? p.out : hbuf;
;     const float* g = p.ln_g + (size_t)(l * 3 + which) * D_;
;     const float* b = p.ln_b + (size_t)(l * 3 + which) * D_;
;     const int lane = TIDX & 63, wave = wave_();
;     const int stride = gridDim.x * 4;
;     int row = blockIdx.x * 4 + wave;
;     f32x4 nx[4];
;     if (row < T_) {
; #pragma unroll
;         for (int i = 0; i < 4; ++i) nx[i] = *(const f32x4*)(hbuf + (size_t)row * D_ + i * 256 + lane * 4);
;     }
;     for (; row < T_; row += stride) {
;         f32x4 v[4];
; #pragma unroll
;         for (int i = 0; i < 4; ++i) v[i] = nx[i];
;         const int rn = row + stride < T_ ? row + stride : row;
; #pragma unroll
;         for (int i = 0; i < 4; ++i) nx[i] = *(const f32x4*)(hbuf + (size_t)rn * D_ + i * 256 + lane * 4);
;         float s = 0.f;
; #pragma unroll
;         for (int i = 0; i < 4; ++i) s += (v[i][0] + v[i][1]) + (v[i][2] + v[i][3]);
; #pragma unroll
;         for (int o = 32; o > 0; o >>= 1) s += __shfl_xor(s, o);
;         const float mu = s * (1.0f / 1024.0f);
;         float q = 0.f;
; #pragma unroll
;         for (int i = 0; i < 4; ++i) { const f32x4 d = v[i] - mu; q += (d[0] * d[0] + d[1] * d[1]) + (d[2] * d[2] + d[3] * d[3]); }
; #pragma unroll
;         for (int o = 32; o > 0; o >>= 1) q += __shfl_xor(q, o);
;         const float rstd = rsqrtf(q * (1.0f / 1024.0f) + 1e-5f);
; #pragma unroll
;         for (int i = 0; i < 4; ++i) {
;             const int c0 = i * 256 + lane * 4;
;             const f32x4 gg = *(const f32x4*)(g + c0), bb = *(const f32x4*)(b + c0);
;             const f32x4 o = (v[i] - mu) * rstd * gg + bb;
;             if (last) *(f32x4*)(dst + (size_t)row * D_ + c0) = o;
;             else { u32x2 pk; pk.x = pk_bf16(o[0], o[1]); pk.y = pk_bf16(o[2], o[3]); *(u32x2*)(hb + (size_t)row * D_ + c0) = pk; }
;         }
;         if (!last && lane == 0) ((f32x2v*)(p.ws + OFF_STATS))[row] = (f32x2v){mu, rstd};
;     }
.LBB0_722:
	s_load_dword s0, s[18:19], 0x0
	v_readlane_b32 s4, v220, 1
	s_mul_i32 s4, s4, 3
	s_add_i32 s4, s4, s52
	s_lshl_b32 s4, s4, 12
	v_readlane_b32 s38, v222, 0
	v_readlane_b32 s39, v222, 1
	v_readlane_b32 s40, v222, 2
	v_readlane_b32 s41, v222, 3
	s_add_u32 s38, s38, s4
	s_addc_u32 s39, s39, 0
	s_add_u32 s40, s40, s4
	s_addc_u32 s41, s41, 0
	v_and_b32_e32 v60, 63, v133
	v_lshlrev_b32_e32 v61, 4, v60
	v_lshlrev_b32_e32 v62, 3, v60
	v_mov_b32_e32 v63, 0
	global_load_dwordx4 v[64:67], v61, s[38:39]
	global_load_dwordx4 v[68:71], v61, s[38:39] offset:1024
	global_load_dwordx4 v[72:75], v61, s[38:39] offset:2048
	global_load_dwordx4 v[76:79], v61, s[38:39] offset:3072
	global_load_dwordx4 v[80:83], v61, s[40:41]
	global_load_dwordx4 v[84:87], v61, s[40:41] offset:1024
	global_load_dwordx4 v[88:91], v61, s[40:41] offset:2048
	global_load_dwordx4 v[92:95], v61, s[40:41] offset:3072
	v_readfirstlane_b32 s6, v133
	s_nop 1
	s_lshr_b32 s6, s6, 6
	s_lshl_b32 s10, s2, 2
	s_add_i32 s10, s10, s6
	s_add_u32 s42, s8, 0xa218000
	s_addc_u32 s43, s9, 0
	s_add_u32 s44, s8, 0xe218000
	s_addc_u32 s45, s9, 0
	v_readlane_b32 s46, v223, 6
	v_readlane_b32 s47, v223, 7
	s_add_u32 s48, s8, 0x15e1c000
	s_addc_u32 s49, s9, 0
	s_cmp_eq_u32 s74, 52
	s_cselect_b32 s14, 1, 0
	s_waitcnt lgkmcnt(0)
	s_lshl_b32 s11, s0, 2
	s_mov_b32 s15, 0
	s_cmpk_eq_i32 s11, 0x800
	s_cbranch_scc0 .Lln_generic
	s_add_i32 s4, s10, 0
	s_lshl_b32 s4, s4, 12
	s_add_u32 s24, s42, s4
	s_addc_u32 s25, s43, 0
	global_load_dwordx4 v[2:5], v61, s[24:25]
	global_load_dwordx4 v[6:9], v61, s[24:25] offset:1024
	global_load_dwordx4 v[10:13], v61, s[24:25] offset:2048
	global_load_dwordx4 v[14:17], v61, s[24:25] offset:3072
	s_add_i32 s4, s10, 2048
	s_lshl_b32 s4, s4, 12
	s_add_u32 s24, s42, s4
	s_addc_u32 s25, s43, 0
	global_load_dwordx4 v[18:21], v61, s[24:25]
	global_load_dwordx4 v[22:25], v61, s[24:25] offset:1024
	global_load_dwordx4 v[26:29], v61, s[24:25] offset:2048
	global_load_dwordx4 v[30:33], v61, s[24:25] offset:3072
	s_add_i32 s4, s10, 4096
	s_lshl_b32 s4, s4, 12
	s_add_u32 s24, s42, s4
	s_addc_u32 s25, s43, 0
	global_load_dwordx4 v[96:99], v61, s[24:25]
	global_load_dwordx4 v[100:103], v61, s[24:25] offset:1024
	global_load_dwordx4 v[104:107], v61, s[24:25] offset:2048
	global_load_dwordx4 v[108:111], v61, s[24:25] offset:3072
	s_waitcnt vmcnt(8)
	v_add_f32_e32 v36, v2, v3
	v_add_f32_e32 v37, v4, v5
	v_add_f32_e32 v34, v36, v37
	v_add_f32_e32 v36, v6, v7
	v_add_f32_e32 v37, v8, v9
	v_add_f32_e32 v36, v36, v37
	v_add_f32_e32 v34, v34, v36
	v_add_f32_e32 v36, v10, v11
	v_add_f32_e32 v37, v12, v13
	v_add_f32_e32 v36, v36, v37
	v_add_f32_e32 v34, v34, v36
	v_add_f32_e32 v36, v14, v15
	v_add_f32_e32 v37, v16, v17
	v_add_f32_e32 v36, v36, v37
	v_add_f32_e32 v34, v34, v36
	s_nop 1
	v_add_f32_dpp v34, v34, v34 quad_perm:[1,0,3,2] row_mask:0xf bank_mask:0xf
	s_nop 1
	v_add_f32_dpp v34, v34, v34 quad_perm:[2,3,0,1] row_mask:0xf bank_mask:0xf
	s_nop 1
	v_add_f32_dpp v34, v34, v34 row_half_mirror row_mask:0xf bank_mask:0xf
	s_nop 1
	v_add_f32_dpp v34, v34, v34 row_mirror row_mask:0xf bank_mask:0xf
	s_nop 1
	v_mov_b32_e32 v38, v34
	s_nop 1
	v_permlane16_swap_b32_e32 v38, v34
	s_nop 1
	v_add_f32_e32 v34, v38, v34
	v_mov_b32_e32 v38, v34
	s_nop 1
	v_permlane32_swap_b32_e32 v38, v34
	s_nop 1
	v_add_f32_e32 v34, v38, v34
	v_fmac_f32_e32 v2, 0xba800000, v34
	v_fmac_f32_e32 v3, 0xba800000, v34
	v_fmac_f32_e32 v4, 0xba800000, v34
	v_fmac_f32_e32 v5, 0xba800000, v34
	v_fmac_f32_e32 v6, 0xba800000, v34
	v_fmac_f32_e32 v7, 0xba800000, v34
	v_fmac_f32_e32 v8, 0xba800000, v34
	v_fmac_f32_e32 v9, 0xba800000, v34
	v_fmac_f32_e32 v10, 0xba800000, v34
	v_fmac_f32_e32 v11, 0xba800000, v34
	v_fmac_f32_e32 v12, 0xba800000, v34
	v_fmac_f32_e32 v13, 0xba800000, v34
	v_fmac_f32_e32 v14, 0xba800000, v34
	v_fmac_f32_e32 v15, 0xba800000, v34
	v_fmac_f32_e32 v16, 0xba800000, v34
	v_fmac_f32_e32 v17, 0xba800000, v34
	v_mul_f32_e32 v36, v2, v2
	v_fmac_f32_e32 v36, v3, v3
	v_mul_f32_e32 v37, v4, v4
	v_fmac_f32_e32 v37, v5, v5
	v_add_f32_e32 v35, v36, v37
	v_mul_f32_e32 v36, v6, v6
	v_fmac_f32_e32 v36, v7, v7
	v_mul_f32_e32 v37, v8, v8
	v_fmac_f32_e32 v37, v9, v9
	v_add_f32_e32 v36, v36, v37
	v_add_f32_e32 v35, v35, v36
	v_mul_f32_e32 v36, v10, v10
	v_fmac_f32_e32 v36, v11, v11
	v_mul_f32_e32 v37, v12, v12
	v_fmac_f32_e32 v37, v13, v13
	v_add_f32_e32 v36, v36, v37
	v_add_f32_e32 v35, v35, v36
	v_mul_f32_e32 v36, v14, v14
	v_fmac_f32_e32 v36, v15, v15
	v_mul_f32_e32 v37, v16, v16
	v_fmac_f32_e32 v37, v17, v17
	v_add_f32_e32 v36, v36, v37
	v_add_f32_e32 v35, v35, v36
	s_nop 1
	v_add_f32_dpp v35, v35, v35 quad_perm:[1,0,3,2] row_mask:0xf bank_mask:0xf
	s_nop 1
	v_add_f32_dpp v35, v35, v35 quad_perm:[2,3,0,1] row_mask:0xf bank_mask:0xf
	s_nop 1
	v_add_f32_dpp v35, v35, v35 row_half_mirror row_mask:0xf bank_mask:0xf
	s_nop 1
	v_add_f32_dpp v35, v35, v35 row_mirror row_mask:0xf bank_mask:0xf
	s_nop 1
	v_mov_b32_e32 v38, v35
	s_nop 1
	v_permlane16_swap_b32_e32 v38, v35
	s_nop 1
	v_add_f32_e32 v35, v38, v35
	v_mov_b32_e32 v38, v35
	s_nop 1
	v_permlane32_swap_b32_e32 v38, v35
	s_nop 1
	v_add_f32_e32 v35, v38, v35
	v_fmamk_f32 v35, v35, 0x3a800000, v137
	v_rsq_f32_e32 v35, v35
	v_mul_f32_e32 v34, 0x3a800000, v34
	s_nop 0
	v_mul_f32_e32 v2, v2, v35
	v_mul_f32_e32 v3, v3, v35
	v_mul_f32_e32 v4, v4, v35
	v_mul_f32_e32 v5, v5, v35
	v_mul_f32_e32 v6, v6, v35
	v_mul_f32_e32 v7, v7, v35
	v_mul_f32_e32 v8, v8, v35
	v_mul_f32_e32 v9, v9, v35
	v_mul_f32_e32 v10, v10, v35
	v_mul_f32_e32 v11, v11, v35
	v_mul_f32_e32 v12, v12, v35
	v_mul_f32_e32 v13, v13, v35
	v_mul_f32_e32 v14, v14, v35
	v_mul_f32_e32 v15, v15, v35
	v_mul_f32_e32 v16, v16, v35
	v_mul_f32_e32 v17, v17, v35
	v_fma_f32 v2, v64, v2, v80
	v_fma_f32 v3, v65, v3, v81
	v_fma_f32 v4, v66, v4, v82
	v_fma_f32 v5, v67, v5, v83
	v_fma_f32 v6, v68, v6, v84
	v_fma_f32 v7, v69, v7, v85
	v_fma_f32 v8, v70, v8, v86
	v_fma_f32 v9, v71, v9, v87
	v_fma_f32 v10, v72, v10, v88
	v_fma_f32 v11, v73, v11, v89
	v_fma_f32 v12, v74, v12, v90
	v_fma_f32 v13, v75, v13, v91
	v_fma_f32 v14, v76, v14, v92
	v_fma_f32 v15, v77, v15, v93
	v_fma_f32 v16, v78, v16, v94
	v_fma_f32 v17, v79, v17, v95
	s_add_i32 s30, s10, 0
	s_cmp_eq_u32 s14, 1
	s_cbranch_scc1 .Lln3_last_0
	s_lshl_b32 s4, s30, 11
	s_add_u32 s26, s44, s4
	s_addc_u32 s27, s45, 0
	v_cvt_pk_bf16_f32 v40, v2, v3
	v_cvt_pk_bf16_f32 v41, v4, v5
	global_store_dwordx2 v62, v[40:41], s[26:27]
	v_cvt_pk_bf16_f32 v42, v6, v7
	v_cvt_pk_bf16_f32 v43, v8, v9
	global_store_dwordx2 v62, v[42:43], s[26:27] offset:512
	v_cvt_pk_bf16_f32 v44, v10, v11
	v_cvt_pk_bf16_f32 v45, v12, v13
	global_store_dwordx2 v62, v[44:45], s[26:27] offset:1024
	v_cvt_pk_bf16_f32 v46, v14, v15
	v_cvt_pk_bf16_f32 v47, v16, v17
	global_store_dwordx2 v62, v[46:47], s[26:27] offset:1536
	s_lshl_b32 s4, s30, 3
	s_add_u32 s26, s48, s4
	s_addc_u32 s27, s49, 0
	s_mov_b64 s[54:55], exec
	v_cmp_eq_u32_e32 vcc, 0, v60
	s_and_b64 exec, exec, vcc
	global_store_dwordx2 v63, v[34:35], s[26:27]
	s_mov_b64 exec, s[54:55]
	s_branch .Lln3_next_0
; DEVI unsigned pk_bf16(float lo, float hi) { const bf16x2n r = __builtin_convertvector((f32x2v){lo, hi}, bf16x2n); return __builtin_bit_cast(unsigned, r); }
; DEVI void phase_ln(const Params& p, int l, int which, bool last) {
;     ...
;     for (; row < T_; row += stride) {
;         f32x4 v[4];
; #pragma unroll
;         for (int i = 0; i < 4; ++i) v[i] = nx[i];
;         const int rn = row + stride < T_ ? row + stride : row;
; #pragma unroll
;         for (int i = 0; i < 4; ++i) nx[i] = *(const f32x4*)(hbuf + (size_t)rn * D_ + i * 256 + lane * 4);
;         float s = 0.f;
; #pragma unroll
;         for (int i = 0; i < 4; ++i) s += (v[i][0] + v[i][1]) + (v[i][2] + v[i][3]);
; #pragma unroll
;         for (int o = 32; o > 0; o >>= 1) s += __shfl_xor(s, o);
;         const float mu = s * (1.0f / 1024.0f);
;         float q = 0.f;
; #pragma unroll
;         for (int i = 0; i < 4; ++i) { const f32x4 d = v[i] - mu; q += (d[0] * d[0] + d[1] * d[1]) + (d[2] * d[2] + d[3] * d[3]); }
; #pragma unroll
;         for (int o = 32; o > 0; o >>= 1) q += __shfl_xor(q, o);
;         const float rstd = rsqrtf(q * (1.0f / 1024.0f) + 1e-5f);
; #pragma unroll
;         for (int i = 0; i < 4; ++i) {
;             const int c0 = i * 256 + lane * 4;
;             const f32x4 gg = *(const f32x4*)(g + c0), bb = *(const f32x4*)(b + c0);
;             const f32x4 o = (v[i] - mu) * rstd * gg + bb;
;             if (last) *(f32x4*)(dst + (size_t)row * D_ + c0) = o;
;             else { u32x2 pk; pk.x = pk_bf16(o[0], o[1]); pk.y = pk_bf16(o[2], o[3]); *(u32x2*)(hb + (size_t)row * D_ + c0) = pk; }
;         }
;         if (!last && lane == 0) ((f32x2v*)(p.ws + OFF_STATS))[row] = (f32x2v){mu, rstd};
;     }
.Lln3_last_0:
	s_lshl_b32 s4, s30, 12
	s_add_u32 s26, s46, s4
	s_addc_u32 s27, s47, 0
	global_store_dwordx4 v61, v[2:5], s[26:27]
	global_store_dwordx4 v61, v[6:9], s[26:27] offset:1024
	global_store_dwordx4 v61, v[10:13], s[26:27] offset:2048
	global_store_dwordx4 v61, v[14:17], s[26:27] offset:3072
.Lln3_next_0:
	s_nop 1
	s_add_i32 s4, s10, 6144
	s_lshl_b32 s4, s4, 12
	s_add_u32 s24, s42, s4
	s_addc_u32 s25, s43, 0
	global_load_dwordx4 v[2:5], v61, s[24:25]
	global_load_dwordx4 v[6:9], v61, s[24:25] offset:1024
	global_load_dwordx4 v[10:13], v61, s[24:25] offset:2048
	global_load_dwordx4 v[14:17], v61, s[24:25] offset:3072
	s_waitcnt vmcnt(12)
	v_add_f32_e32 v36, v18, v19
	v_add_f32_e32 v37, v20, v21
	v_add_f32_e32 v34, v36, v37
	v_add_f32_e32 v36, v22, v23
	v_add_f32_e32 v37, v24, v25
	v_add_f32_e32 v36, v36, v37
	v_add_f32_e32 v34, v34, v36
	v_add_f32_e32 v36, v26, v27
	v_add_f32_e32 v37, v28, v29
	v_add_f32_e32 v36, v36, v37
	v_add_f32_e32 v34, v34, v36
	v_add_f32_e32 v36, v30, v31
	v_add_f32_e32 v37, v32, v33
	v_add_f32_e32 v36, v36, v37
	v_add_f32_e32 v34, v34, v36
	s_nop 1
	v_add_f32_dpp v34, v34, v34 quad_perm:[1,0,3,2] row_mask:0xf bank_mask:0xf
	s_nop 1
	v_add_f32_dpp v34, v34, v34 quad_perm:[2,3,0,1] row_mask:0xf bank_mask:0xf
	s_nop 1
	v_add_f32_dpp v34, v34, v34 row_half_mirror row_mask:0xf bank_mask:0xf
	s_nop 1
	v_add_f32_dpp v34, v34, v34 row_mirror row_mask:0xf bank_mask:0xf
	s_nop 1
	v_mov_b32_e32 v38, v34
	s_nop 1
	v_permlane16_swap_b32_e32 v38, v34
	s_nop 1
	v_add_f32_e32 v34, v38, v34
	v_mov_b32_e32 v38, v34
	s_nop 1
	v_permlane32_swap_b32_e32 v38, v34
	s_nop 1
	v_add_f32_e32 v34, v38, v34
	v_fmac_f32_e32 v18, 0xba800000, v34
	v_fmac_f32_e32 v19, 0xba800000, v34
	v_fmac_f32_e32 v20, 0xba800000, v34
	v_fmac_f32_e32 v21, 0xba800000, v34
	v_fmac_f32_e32 v22, 0xba800000, v34
	v_fmac_f32_e32 v23, 0xba800000, v34
	v_fmac_f32_e32 v24, 0xba800000, v34
	v_fmac_f32_e32 v25, 0xba800000, v34
	v_fmac_f32_e32 v26, 0xba800000, v34
	v_fmac_f32_e32 v27, 0xba800000, v34
	v_fmac_f32_e32 v28, 0xba800000, v34
	v_fmac_f32_e32 v29, 0xba800000, v34
	v_fmac_f32_e32 v30, 0xba800000, v34
	v_fmac_f32_e32 v31, 0xba800000, v34
	v_fmac_f32_e32 v32, 0xba800000, v34
	v_fmac_f32_e32 v33, 0xba800000, v34
	v_mul_f32_e32 v36, v18, v18
	v_fmac_f32_e32 v36, v19, v19
	v_mul_f32_e32 v37, v20, v20
	v_fmac_f32_e32 v37, v21, v21
	v_add_f32_e32 v35, v36, v37
	v_mul_f32_e32 v36, v22, v22
	v_fmac_f32_e32 v36, v23, v23
	v_mul_f32_e32 v37, v24, v24
	v_fmac_f32_e32 v37, v25, v25
	v_add_f32_e32 v36, v36, v37
	v_add_f32_e32 v35, v35, v36
	v_mul_f32_e32 v36, v26, v26
	v_fmac_f32_e32 v36, v27, v27
	v_mul_f32_e32 v37, v28, v28
	v_fmac_f32_e32 v37, v29, v29
	v_add_f32_e32 v36, v36, v37
	v_add_f32_e32 v35, v35, v36
	v_mul_f32_e32 v36, v30, v30
	v_fmac_f32_e32 v36, v31, v31
	v_mul_f32_e32 v37, v32, v32
	v_fmac_f32_e32 v37, v33, v33
	v_add_f32_e32 v36, v36, v37
	v_add_f32_e32 v35, v35, v36
	s_nop 1
	v_add_f32_dpp v35, v35, v35 quad_perm:[1,0,3,2] row_mask:0xf bank_mask:0xf
	s_nop 1
	v_add_f32_dpp v35, v35, v35 quad_perm:[2,3,0,1] row_mask:0xf bank_mask:0xf
	s_nop 1
	v_add_f32_dpp v35, v35, v35 row_half_mirror row_mask:0xf bank_mask:0xf
	s_nop 1
	v_add_f32_dpp v35, v35, v35 row_mirror row_mask:0xf bank_mask:0xf
	s_nop 1
	v_mov_b32_e32 v38, v35
	s_nop 1
	v_permlane16_swap_b32_e32 v38, v35
	s_nop 1
	v_add_f32_e32 v35, v38, v35
	v_mov_b32_e32 v38, v35
	s_nop 1
	v_permlane32_swap_b32_e32 v38, v35
	s_nop 1
	v_add_f32_e32 v35, v38, v35
	v_fmamk_f32 v35, v35, 0x3a800000, v137
	v_rsq_f32_e32 v35, v35
	v_mul_f32_e32 v34, 0x3a800000, v34
	s_nop 0
	v_mul_f32_e32 v18, v18, v35
	v_mul_f32_e32 v19, v19, v35
	v_mul_f32_e32 v20, v20, v35
	v_mul_f32_e32 v21, v21, v35
	v_mul_f32_e32 v22, v22, v35
	v_mul_f32_e32 v23, v23, v35
	v_mul_f32_e32 v24, v24, v35
	v_mul_f32_e32 v25, v25, v35
	v_mul_f32_e32 v26, v26, v35
	v_mul_f32_e32 v27, v27, v35
	v_mul_f32_e32 v28, v28, v35
	v_mul_f32_e32 v29, v29, v35
	v_mul_f32_e32 v30, v30, v35
	v_mul_f32_e32 v31, v31, v35
	v_mul_f32_e32 v32, v32, v35
	v_mul_f32_e32 v33, v33, v35
	v_fma_f32 v18, v64, v18, v80
	v_fma_f32 v19, v65, v19, v81
	v_fma_f32 v20, v66, v20, v82
	v_fma_f32 v21, v67, v21, v83
	v_fma_f32 v22, v68, v22, v84
	v_fma_f32 v23, v69, v23, v85
	v_fma_f32 v24, v70, v24, v86
	v_fma_f32 v25, v71, v25, v87
	v_fma_f32 v26, v72, v26, v88
	v_fma_f32 v27, v73, v27, v89
	v_fma_f32 v28, v74, v28, v90
	v_fma_f32 v29, v75, v29, v91
	v_fma_f32 v30, v76, v30, v92
	v_fma_f32 v31, v77, v31, v93
	v_fma_f32 v32, v78, v32, v94
	v_fma_f32 v33, v79, v33, v95
	s_add_i32 s30, s10, 2048
	s_cmp_eq_u32 s14, 1
	s_cbranch_scc1 .Lln3_last_1
	s_lshl_b32 s4, s30, 11
	s_add_u32 s26, s44, s4
	s_addc_u32 s27, s45, 0
	v_cvt_pk_bf16_f32 v40, v18, v19
	v_cvt_pk_bf16_f32 v41, v20, v21
	global_store_dwordx2 v62, v[40:41], s[26:27]
	v_cvt_pk_bf16_f32 v42, v22, v23
	v_cvt_pk_bf16_f32 v43, v24, v25
	global_store_dwordx2 v62, v[42:43], s[26:27] offset:512
	v_cvt_pk_bf16_f32 v44, v26, v27
	v_cvt_pk_bf16_f32 v45, v28, v29
	global_store_dwordx2 v62, v[44:45], s[26:27] offset:1024
	v_cvt_pk_bf16_f32 v46, v30, v31
	v_cvt_pk_bf16_f32 v47, v32, v33
	global_store_dwordx2 v62, v[46:47], s[26:27] offset:1536
	s_lshl_b32 s4, s30, 3
	s_add_u32 s26, s48, s4
	s_addc_u32 s27, s49, 0
	s_mov_b64 s[54:55], exec
	v_cmp_eq_u32_e32 vcc, 0, v60
	s_and_b64 exec, exec, vcc
	global_store_dwordx2 v63, v[34:35], s[26:27]
	s_mov_b64 exec, s[54:55]
	s_branch .Lln3_next_1
.Lln3_last_1:
	s_lshl_b32 s4, s30, 12
	s_add_u32 s26, s46, s4
	s_addc_u32 s27, s47, 0
	global_store_dwordx4 v61, v[18:21], s[26:27]
	global_store_dwordx4 v61, v[22:25], s[26:27] offset:1024
	global_store_dwordx4 v61, v[26:29], s[26:27] offset:2048
	global_store_dwordx4 v61, v[30:33], s[26:27] offset:3072
; DEVI unsigned pk_bf16(float lo, float hi) { const bf16x2n r = __builtin_convertvector((f32x2v){lo, hi}, bf16x2n); return __builtin_bit_cast(unsigned, r); }
; DEVI void phase_ln(const Params& p, int l, int which, bool last) {
;     ...
;     for (; row < T_; row += stride) {
;         f32x4 v[4];
; #pragma unroll
;         for (int i = 0; i < 4; ++i) v[i] = nx[i];
;         const int rn = row + stride < T_ ? row + stride : row;
; #pragma unroll
;         for (int i = 0; i < 4; ++i) nx[i] = *(const f32x4*)(hbuf + (size_t)rn * D_ + i * 256 + lane * 4);
;         float s = 0.f;
; #pragma unroll
;         for (int i = 0; i < 4; ++i) s += (v[i][0] + v[i][1]) + (v[i][2] + v[i][3]);
; #pragma unroll
;         for (int o = 32; o > 0; o >>= 1) s += __shfl_xor(s, o);
;         const float mu = s * (1.0f / 1024.0f);
;         float q = 0.f;
; #pragma unroll
;         for (int i = 0; i < 4; ++i) { const f32x4 d = v[i] - mu; q += (d[0] * d[0] + d[1] * d[1]) + (d[2] * d[2] + d[3] * d[3]); }
; #pragma unroll
;         for (int o = 32; o > 0; o >>= 1) q += __shfl_xor(q, o);
;         const float rstd = rsqrtf(q * (1.0f / 1024.0f) + 1e-5f);
; #pragma unroll
;         for (int i = 0; i < 4; ++i) {
;             const int c0 = i * 256 + lane * 4;
;             const f32x4 gg = *(const f32x4*)(g + c0), bb = *(const f32x4*)(b + c0);
;             const f32x4 o = (v[i] - mu) * rstd * gg + bb;
;             if (last) *(f32x4*)(dst + (size_t)row * D_ + c0) = o;
;             else { u32x2 pk; pk.x = pk_bf16(o[0], o[1]); pk.y = pk_bf16(o[2], o[3]); *(u32x2*)(hb + (size_t)row * D_ + c0) = pk; }
;         }
;         if (!last && lane == 0) ((f32x2v*)(p.ws + OFF_STATS))[row] = (f32x2v){mu, rstd};
;     }
.Lln3_next_1:
	s_nop 1
	s_add_i32 s4, s10, 8192
	s_lshl_b32 s4, s4, 12
	s_add_u32 s24, s42, s4
	s_addc_u32 s25, s43, 0
	global_load_dwordx4 v[18:21], v61, s[24:25]
	global_load_dwordx4 v[22:25], v61, s[24:25] offset:1024
	global_load_dwordx4 v[26:29], v61, s[24:25] offset:2048
	global_load_dwordx4 v[30:33], v61, s[24:25] offset:3072
	s_waitcnt vmcnt(16)
	v_add_f32_e32 v36, v96, v97
	v_add_f32_e32 v37, v98, v99
	v_add_f32_e32 v34, v36, v37
	v_add_f32_e32 v36, v100, v101
	v_add_f32_e32 v37, v102, v103
	v_add_f32_e32 v36, v36, v37
	v_add_f32_e32 v34, v34, v36
	v_add_f32_e32 v36, v104, v105
	v_add_f32_e32 v37, v106, v107
	v_add_f32_e32 v36, v36, v37
	v_add_f32_e32 v34, v34, v36
	v_add_f32_e32 v36, v108, v109
	v_add_f32_e32 v37, v110, v111
	v_add_f32_e32 v36, v36, v37
	v_add_f32_e32 v34, v34, v36
	s_nop 1
	v_add_f32_dpp v34, v34, v34 quad_perm:[1,0,3,2] row_mask:0xf bank_mask:0xf
	s_nop 1
	v_add_f32_dpp v34, v34, v34 quad_perm:[2,3,0,1] row_mask:0xf bank_mask:0xf
	s_nop 1
	v_add_f32_dpp v34, v34, v34 row_half_mirror row_mask:0xf bank_mask:0xf
	s_nop 1
	v_add_f32_dpp v34, v34, v34 row_mirror row_mask:0xf bank_mask:0xf
	s_nop 1
	v_mov_b32_e32 v38, v34
	s_nop 1
	v_permlane16_swap_b32_e32 v38, v34
	s_nop 1
	v_add_f32_e32 v34, v38, v34
	v_mov_b32_e32 v38, v34
	s_nop 1
	v_permlane32_swap_b32_e32 v38, v34
	s_nop 1
	v_add_f32_e32 v34, v38, v34
	v_fmac_f32_e32 v96, 0xba800000, v34
	v_fmac_f32_e32 v97, 0xba800000, v34
	v_fmac_f32_e32 v98, 0xba800000, v34
	v_fmac_f32_e32 v99, 0xba800000, v34
	v_fmac_f32_e32 v100, 0xba800000, v34
	v_fmac_f32_e32 v101, 0xba800000, v34
	v_fmac_f32_e32 v102, 0xba800000, v34
	v_fmac_f32_e32 v103, 0xba800000, v34
	v_fmac_f32_e32 v104, 0xba800000, v34
	v_fmac_f32_e32 v105, 0xba800000, v34
	v_fmac_f32_e32 v106, 0xba800000, v34
	v_fmac_f32_e32 v107, 0xba800000, v34
	v_fmac_f32_e32 v108, 0xba800000, v34
	v_fmac_f32_e32 v109, 0xba800000, v34
	v_fmac_f32_e32 v110, 0xba800000, v34
	v_fmac_f32_e32 v111, 0xba800000, v34
	v_mul_f32_e32 v36, v96, v96
	v_fmac_f32_e32 v36, v97, v97
	v_mul_f32_e32 v37, v98, v98
	v_fmac_f32_e32 v37, v99, v99
	v_add_f32_e32 v35, v36, v37
	v_mul_f32_e32 v36, v100, v100
	v_fmac_f32_e32 v36, v101, v101
	v_mul_f32_e32 v37, v102, v102
	v_fmac_f32_e32 v37, v103, v103
	v_add_f32_e32 v36, v36, v37
	v_add_f32_e32 v35, v35, v36
	v_mul_f32_e32 v36, v104, v104
	v_fmac_f32_e32 v36, v105, v105
	v_mul_f32_e32 v37, v106, v106
	v_fmac_f32_e32 v37, v107, v107
	v_add_f32_e32 v36, v36, v37
	v_add_f32_e32 v35, v35, v36
	v_mul_f32_e32 v36, v108, v108
	v_fmac_f32_e32 v36, v109, v109
	v_mul_f32_e32 v37, v110, v110
	v_fmac_f32_e32 v37, v111, v111
	v_add_f32_e32 v36, v36, v37
	v_add_f32_e32 v35, v35, v36
	s_nop 1
	v_add_f32_dpp v35, v35, v35 quad_perm:[1,0,3,2] row_mask:0xf bank_mask:0xf
	s_nop 1
	v_add_f32_dpp v35, v35, v35 quad_perm:[2,3,0,1] row_mask:0xf bank_mask:0xf
	s_nop 1
	v_add_f32_dpp v35, v35, v35 row_half_mirror row_mask:0xf bank_mask:0xf
	s_nop 1
	v_add_f32_dpp v35, v35, v35 row_mirror row_mask:0xf bank_mask:0xf
	s_nop 1
	v_mov_b32_e32 v38, v35
	s_nop 1
	v_permlane16_swap_b32_e32 v38, v35
	s_nop 1
	v_add_f32_e32 v35, v38, v35
	v_mov_b32_e32 v38, v35
	s_nop 1
	v_permlane32_swap_b32_e32 v38, v35
	s_nop 1
	v_add_f32_e32 v35, v38, v35
	v_fmamk_f32 v35, v35, 0x3a800000, v137
	v_rsq_f32_e32 v35, v35
	v_mul_f32_e32 v34, 0x3a800000, v34
	s_nop 0
	v_mul_f32_e32 v96, v96, v35
	v_mul_f32_e32 v97, v97, v35
	v_mul_f32_e32 v98, v98, v35
	v_mul_f32_e32 v99, v99, v35
	v_mul_f32_e32 v100, v100, v35
	v_mul_f32_e32 v101, v101, v35
	v_mul_f32_e32 v102, v102, v35
	v_mul_f32_e32 v103, v103, v35
	v_mul_f32_e32 v104, v104, v35
	v_mul_f32_e32 v105, v105, v35
	v_mul_f32_e32 v106, v106, v35
	v_mul_f32_e32 v107, v107, v35
	v_mul_f32_e32 v108, v108, v35
	v_mul_f32_e32 v109, v109, v35
	v_mul_f32_e32 v110, v110, v35
	v_mul_f32_e32 v111, v111, v35
	v_fma_f32 v96, v64, v96, v80
	v_fma_f32 v97, v65, v97, v81
	v_fma_f32 v98, v66, v98, v82
	v_fma_f32 v99, v67, v99, v83
	v_fma_f32 v100, v68, v100, v84
	v_fma_f32 v101, v69, v101, v85
	v_fma_f32 v102, v70, v102, v86
	v_fma_f32 v103, v71, v103, v87
	v_fma_f32 v104, v72, v104, v88
	v_fma_f32 v105, v73, v105, v89
	v_fma_f32 v106, v74, v106, v90
	v_fma_f32 v107, v75, v107, v91
	v_fma_f32 v108, v76, v108, v92
	v_fma_f32 v109, v77, v109, v93
	v_fma_f32 v110, v78, v110, v94
	v_fma_f32 v111, v79, v111, v95
	s_add_i32 s30, s10, 4096
	s_cmp_eq_u32 s14, 1
	s_cbranch_scc1 .Lln3_last_2
	s_lshl_b32 s4, s30, 11
	s_add_u32 s26, s44, s4
	s_addc_u32 s27, s45, 0
	v_cvt_pk_bf16_f32 v40, v96, v97
	v_cvt_pk_bf16_f32 v41, v98, v99
	global_store_dwordx2 v62, v[40:41], s[26:27]
	v_cvt_pk_bf16_f32 v42, v100, v101
	v_cvt_pk_bf16_f32 v43, v102, v103
	global_store_dwordx2 v62, v[42:43], s[26:27] offset:512
	v_cvt_pk_bf16_f32 v44, v104, v105
	v_cvt_pk_bf16_f32 v45, v106, v107
	global_store_dwordx2 v62, v[44:45], s[26:27] offset:1024
	v_cvt_pk_bf16_f32 v46, v108, v109
	v_cvt_pk_bf16_f32 v47, v110, v111
	global_store_dwordx2 v62, v[46:47], s[26:27] offset:1536
	s_lshl_b32 s4, s30, 3
	s_add_u32 s26, s48, s4
	s_addc_u32 s27, s49, 0
	s_mov_b64 s[54:55], exec
	v_cmp_eq_u32_e32 vcc, 0, v60
	s_and_b64 exec, exec, vcc
	global_store_dwordx2 v63, v[34:35], s[26:27]
	s_mov_b64 exec, s[54:55]
	s_branch .Lln3_next_2
; DEVI unsigned pk_bf16(float lo, float hi) { const bf16x2n r = __builtin_convertvector((f32x2v){lo, hi}, bf16x2n); return __builtin_bit_cast(unsigned, r); }
; DEVI void phase_ln(const Params& p, int l, int which, bool last) {
;     ...
;     for (; row < T_; row += stride) {
;         f32x4 v[4];
; #pragma unroll
;         for (int i = 0; i < 4; ++i) v[i] = nx[i];
;         const int rn = row + stride < T_ ? row + stride : row;
; #pragma unroll
;         for (int i = 0; i < 4; ++i) nx[i] = *(const f32x4*)(hbuf + (size_t)rn * D_ + i * 256 + lane * 4);
;         float s = 0.f;
; #pragma unroll
;         for (int i = 0; i < 4; ++i) s += (v[i][0] + v[i][1]) + (v[i][2] + v[i][3]);
; #pragma unroll
;         for (int o = 32; o > 0; o >>= 1) s += __shfl_xor(s, o);
;         const float mu = s * (1.0f / 1024.0f);
;         float q = 0.f;
; #pragma unroll
;         for (int i = 0; i < 4; ++i) { const f32x4 d = v[i] - mu; q += (d[0] * d[0] + d[1] * d[1]) + (d[2] * d[2] + d[3] * d[3]); }
; #pragma unroll
;         for (int o = 32; o > 0; o >>= 1) q += __shfl_xor(q, o);
;         const float rstd = rsqrtf(q * (1.0f / 1024.0f) + 1e-5f);
; #pragma unroll
;         for (int i = 0; i < 4; ++i) {
;             const int c0 = i * 256 + lane * 4;
;             const f32x4 gg = *(const f32x4*)(g + c0), bb = *(const f32x4*)(b + c0);
;             const f32x4 o = (v[i] - mu) * rstd * gg + bb;
;             if (last) *(f32x4*)(dst + (size_t)row * D_ + c0) = o;
;             else { u32x2 pk; pk.x = pk_bf16(o[0], o[1]); pk.y = pk_bf16(o[2], o[3]); *(u32x2*)(hb + (size_t)row * D_ + c0) = pk; }
;         }
;         if (!last && lane == 0) ((f32x2v*)(p.ws + OFF_STATS))[row] = (f32x2v){mu, rstd};
;     }
.Lln3_last_2:
	s_lshl_b32 s4, s30, 12
	s_add_u32 s26, s46, s4
	s_addc_u32 s27, s47, 0
	global_store_dwordx4 v61, v[96:99], s[26:27]
	global_store_dwordx4 v61, v[100:103], s[26:27] offset:1024
	global_store_dwordx4 v61, v[104:107], s[26:27] offset:2048
	global_store_dwordx4 v61, v[108:111], s[26:27] offset:3072
.Lln3_next_2:
	s_nop 1
	s_add_i32 s4, s10, 10240
	s_lshl_b32 s4, s4, 12
	s_add_u32 s24, s42, s4
	s_addc_u32 s25, s43, 0
	global_load_dwordx4 v[96:99], v61, s[24:25]
	global_load_dwordx4 v[100:103], v61, s[24:25] offset:1024
	global_load_dwordx4 v[104:107], v61, s[24:25] offset:2048
	global_load_dwordx4 v[108:111], v61, s[24:25] offset:3072
	s_waitcnt vmcnt(16)
	v_add_f32_e32 v36, v2, v3
	v_add_f32_e32 v37, v4, v5
	v_add_f32_e32 v34, v36, v37
	v_add_f32_e32 v36, v6, v7
	v_add_f32_e32 v37, v8, v9
	v_add_f32_e32 v36, v36, v37
	v_add_f32_e32 v34, v34, v36
	v_add_f32_e32 v36, v10, v11
	v_add_f32_e32 v37, v12, v13
	v_add_f32_e32 v36, v36, v37
	v_add_f32_e32 v34, v34, v36
	v_add_f32_e32 v36, v14, v15
	v_add_f32_e32 v37, v16, v17
	v_add_f32_e32 v36, v36, v37
	v_add_f32_e32 v34, v34, v36
	s_nop 1
	v_add_f32_dpp v34, v34, v34 quad_perm:[1,0,3,2] row_mask:0xf bank_mask:0xf
	s_nop 1
	v_add_f32_dpp v34, v34, v34 quad_perm:[2,3,0,1] row_mask:0xf bank_mask:0xf
	s_nop 1
	v_add_f32_dpp v34, v34, v34 row_half_mirror row_mask:0xf bank_mask:0xf
	s_nop 1
	v_add_f32_dpp v34, v34, v34 row_mirror row_mask:0xf bank_mask:0xf
	s_nop 1
	v_mov_b32_e32 v38, v34
	s_nop 1
	v_permlane16_swap_b32_e32 v38, v34
	s_nop 1
	v_add_f32_e32 v34, v38, v34
	v_mov_b32_e32 v38, v34
	s_nop 1
	v_permlane32_swap_b32_e32 v38, v34
	s_nop 1
	v_add_f32_e32 v34, v38, v34
	v_fmac_f32_e32 v2, 0xba800000, v34
	v_fmac_f32_e32 v3, 0xba800000, v34
	v_fmac_f32_e32 v4, 0xba800000, v34
	v_fmac_f32_e32 v5, 0xba800000, v34
	v_fmac_f32_e32 v6, 0xba800000, v34
	v_fmac_f32_e32 v7, 0xba800000, v34
	v_fmac_f32_e32 v8, 0xba800000, v34
	v_fmac_f32_e32 v9, 0xba800000, v34
	v_fmac_f32_e32 v10, 0xba800000, v34
	v_fmac_f32_e32 v11, 0xba800000, v34
	v_fmac_f32_e32 v12, 0xba800000, v34
	v_fmac_f32_e32 v13, 0xba800000, v34
	v_fmac_f32_e32 v14, 0xba800000, v34
	v_fmac_f32_e32 v15, 0xba800000, v34
	v_fmac_f32_e32 v16, 0xba800000, v34
	v_fmac_f32_e32 v17, 0xba800000, v34
	v_mul_f32_e32 v36, v2, v2
	v_fmac_f32_e32 v36, v3, v3
	v_mul_f32_e32 v37, v4, v4
	v_fmac_f32_e32 v37, v5, v5
	v_add_f32_e32 v35, v36, v37
	v_mul_f32_e32 v36, v6, v6
	v_fmac_f32_e32 v36, v7, v7
	v_mul_f32_e32 v37, v8, v8
	v_fmac_f32_e32 v37, v9, v9
	v_add_f32_e32 v36, v36, v37
	v_add_f32_e32 v35, v35, v36
	v_mul_f32_e32 v36, v10, v10
	v_fmac_f32_e32 v36, v11, v11
	v_mul_f32_e32 v37, v12, v12
	v_fmac_f32_e32 v37, v13, v13
	v_add_f32_e32 v36, v36, v37
	v_add_f32_e32 v35, v35, v36
	v_mul_f32_e32 v36, v14, v14
	v_fmac_f32_e32 v36, v15, v15
	v_mul_f32_e32 v37, v16, v16
	v_fmac_f32_e32 v37, v17, v17
	v_add_f32_e32 v36, v36, v37
	v_add_f32_e32 v35, v35, v36
	s_nop 1
	v_add_f32_dpp v35, v35, v35 quad_perm:[1,0,3,2] row_mask:0xf bank_mask:0xf
	s_nop 1
	v_add_f32_dpp v35, v35, v35 quad_perm:[2,3,0,1] row_mask:0xf bank_mask:0xf
	s_nop 1
	v_add_f32_dpp v35, v35, v35 row_half_mirror row_mask:0xf bank_mask:0xf
	s_nop 1
	v_add_f32_dpp v35, v35, v35 row_mirror row_mask:0xf bank_mask:0xf
	s_nop 1
	v_mov_b32_e32 v38, v35
	s_nop 1
	v_permlane16_swap_b32_e32 v38, v35
	s_nop 1
	v_add_f32_e32 v35, v38, v35
	v_mov_b32_e32 v38, v35
	s_nop 1
	v_permlane32_swap_b32_e32 v38, v35
	s_nop 1
	v_add_f32_e32 v35, v38, v35
	v_fmamk_f32 v35, v35, 0x3a800000, v137
	v_rsq_f32_e32 v35, v35
	v_mul_f32_e32 v34, 0x3a800000, v34
	s_nop 0
	v_mul_f32_e32 v2, v2, v35
	v_mul_f32_e32 v3, v3, v35
	v_mul_f32_e32 v4, v4, v35
	v_mul_f32_e32 v5, v5, v35
	v_mul_f32_e32 v6, v6, v35
	v_mul_f32_e32 v7, v7, v35
	v_mul_f32_e32 v8, v8, v35
	v_mul_f32_e32 v9, v9, v35
	v_mul_f32_e32 v10, v10, v35
	v_mul_f32_e32 v11, v11, v35
	v_mul_f32_e32 v12, v12, v35
	v_mul_f32_e32 v13, v13, v35
	v_mul_f32_e32 v14, v14, v35
	v_mul_f32_e32 v15, v15, v35
	v_mul_f32_e32 v16, v16, v35
	v_mul_f32_e32 v17, v17, v35
	v_fma_f32 v2, v64, v2, v80
	v_fma_f32 v3, v65, v3, v81
	v_fma_f32 v4, v66, v4, v82
	v_fma_f32 v5, v67, v5, v83
	v_fma_f32 v6, v68, v6, v84
	v_fma_f32 v7, v69, v7, v85
	v_fma_f32 v8, v70, v8, v86
	v_fma_f32 v9, v71, v9, v87
	v_fma_f32 v10, v72, v10, v88
	v_fma_f32 v11, v73, v11, v89
	v_fma_f32 v12, v74, v12, v90
	v_fma_f32 v13, v75, v13, v91
	v_fma_f32 v14, v76, v14, v92
	v_fma_f32 v15, v77, v15, v93
	v_fma_f32 v16, v78, v16, v94
	v_fma_f32 v17, v79, v17, v95
	s_add_i32 s30, s10, 6144
	s_cmp_eq_u32 s14, 1
	s_cbranch_scc1 .Lln3_last_3
	s_lshl_b32 s4, s30, 11
	s_add_u32 s26, s44, s4
	s_addc_u32 s27, s45, 0
	v_cvt_pk_bf16_f32 v40, v2, v3
	v_cvt_pk_bf16_f32 v41, v4, v5
	global_store_dwordx2 v62, v[40:41], s[26:27]
	v_cvt_pk_bf16_f32 v42, v6, v7
	v_cvt_pk_bf16_f32 v43, v8, v9
	global_store_dwordx2 v62, v[42:43], s[26:27] offset:512
	v_cvt_pk_bf16_f32 v44, v10, v11
	v_cvt_pk_bf16_f32 v45, v12, v13
	global_store_dwordx2 v62, v[44:45], s[26:27] offset:1024
	v_cvt_pk_bf16_f32 v46, v14, v15
	v_cvt_pk_bf16_f32 v47, v16, v17
	global_store_dwordx2 v62, v[46:47], s[26:27] offset:1536
	s_lshl_b32 s4, s30, 3
	s_add_u32 s26, s48, s4
	s_addc_u32 s27, s49, 0
	s_mov_b64 s[54:55], exec
	v_cmp_eq_u32_e32 vcc, 0, v60
	s_and_b64 exec, exec, vcc
	global_store_dwordx2 v63, v[34:35], s[26:27]
	s_mov_b64 exec, s[54:55]
	s_branch .Lln3_next_3

; DEVI unsigned pk_bf16(float lo, float hi) { const bf16x2n r = __builtin_convertvector((f32x2v){lo, hi}, bf16x2n); return __builtin_bit_cast(unsigned, r); }
; DEVI void phase_ln(const Params& p, int l, int which, bool last) {
;     ...
;     for (; row < T_; row += stride) {
;         f32x4 v[4];
; #pragma unroll
;         for (int i = 0; i < 4; ++i) v[i] = nx[i];
;         const int rn = row + stride < T_ ? row + stride : row;
; #pragma unroll
;         for (int i = 0; i < 4; ++i) nx[i] = *(const f32x4*)(hbuf + (size_t)rn * D_ + i * 256 + lane * 4);
;         float s = 0.f;
; #pragma unroll
;         for (int i = 0; i < 4; ++i) s += (v[i][0] + v[i][1]) + (v[i][2] + v[i][3]);
; #pragma unroll
;         for (int o = 32; o > 0; o >>= 1) s += __shfl_xor(s, o);
;         const float mu = s * (1.0f / 1024.0f);
;         float q = 0.f;
; #pragma unroll
;         for (int i = 0; i < 4; ++i) { const f32x4 d = v[i] - mu; q += (d[0] * d[0] + d[1] * d[1]) + (d[2] * d[2] + d[3] * d[3]); }
; #pragma unroll
;         for (int o = 32; o > 0; o >>= 1) q += __shfl_xor(q, o);
;         const float rstd = rsqrtf(q * (1.0f / 1024.0f) + 1e-5f);
; #pragma unroll
;         for (int i = 0; i < 4; ++i) {
;             const int c0 = i * 256 + lane * 4;
;             const f32x4 gg = *(const f32x4*)(g + c0), bb = *(const f32x4*)(b + c0);
;             const f32x4 o = (v[i] - mu) * rstd * gg + bb;
;             if (last) *(f32x4*)(dst + (size_t)row * D_ + c0) = o;
;             else { u32x2 pk; pk.x = pk_bf16(o[0], o[1]); pk.y = pk_bf16(o[2], o[3]); *(u32x2*)(hb + (size_t)row * D_ + c0) = pk; }
;         }
;         if (!last && lane == 0) ((f32x2v*)(p.ws + OFF_STATS))[row] = (f32x2v){mu, rstd};
;     }
.Lln3_next_3:
	s_nop 1
	s_add_i32 s4, s10, 12288
	s_lshl_b32 s4, s4, 12
	s_add_u32 s24, s42, s4
	s_addc_u32 s25, s43, 0
	global_load_dwordx4 v[2:5], v61, s[24:25]
	global_load_dwordx4 v[6:9], v61, s[24:25] offset:1024
	global_load_dwordx4 v[10:13], v61, s[24:25] offset:2048
	global_load_dwordx4 v[14:17], v61, s[24:25] offset:3072
	s_waitcnt vmcnt(16)
	v_add_f32_e32 v36, v18, v19
	v_add_f32_e32 v37, v20, v21
	v_add_f32_e32 v34, v36, v37
	v_add_f32_e32 v36, v22, v23
	v_add_f32_e32 v37, v24, v25
	v_add_f32_e32 v36, v36, v37
	v_add_f32_e32 v34, v34, v36
	v_add_f32_e32 v36, v26, v27
	v_add_f32_e32 v37, v28, v29
	v_add_f32_e32 v36, v36, v37
	v_add_f32_e32 v34, v34, v36
	v_add_f32_e32 v36, v30, v31
	v_add_f32_e32 v37, v32, v33
	v_add_f32_e32 v36, v36, v37
	v_add_f32_e32 v34, v34, v36
	s_nop 1
	v_add_f32_dpp v34, v34, v34 quad_perm:[1,0,3,2] row_mask:0xf bank_mask:0xf
	s_nop 1
	v_add_f32_dpp v34, v34, v34 quad_perm:[2,3,0,1] row_mask:0xf bank_mask:0xf
	s_nop 1
	v_add_f32_dpp v34, v34, v34 row_half_mirror row_mask:0xf bank_mask:0xf
	s_nop 1
	v_add_f32_dpp v34, v34, v34 row_mirror row_mask:0xf bank_mask:0xf
	s_nop 1
	v_mov_b32_e32 v38, v34
	s_nop 1
	v_permlane16_swap_b32_e32 v38, v34
	s_nop 1
	v_add_f32_e32 v34, v38, v34
	v_mov_b32_e32 v38, v34
	s_nop 1
	v_permlane32_swap_b32_e32 v38, v34
	s_nop 1
	v_add_f32_e32 v34, v38, v34
	v_fmac_f32_e32 v18, 0xba800000, v34
	v_fmac_f32_e32 v19, 0xba800000, v34
	v_fmac_f32_e32 v20, 0xba800000, v34
	v_fmac_f32_e32 v21, 0xba800000, v34
	v_fmac_f32_e32 v22, 0xba800000, v34
	v_fmac_f32_e32 v23, 0xba800000, v34
	v_fmac_f32_e32 v24, 0xba800000, v34
	v_fmac_f32_e32 v25, 0xba800000, v34
	v_fmac_f32_e32 v26, 0xba800000, v34
	v_fmac_f32_e32 v27, 0xba800000, v34
	v_fmac_f32_e32 v28, 0xba800000, v34
	v_fmac_f32_e32 v29, 0xba800000, v34
	v_fmac_f32_e32 v30, 0xba800000, v34
	v_fmac_f32_e32 v31, 0xba800000, v34
	v_fmac_f32_e32 v32, 0xba800000, v34
	v_fmac_f32_e32 v33, 0xba800000, v34
	v_mul_f32_e32 v36, v18, v18
	v_fmac_f32_e32 v36, v19, v19
	v_mul_f32_e32 v37, v20, v20
	v_fmac_f32_e32 v37, v21, v21
	v_add_f32_e32 v35, v36, v37
	v_mul_f32_e32 v36, v22, v22
	v_fmac_f32_e32 v36, v23, v23
	v_mul_f32_e32 v37, v24, v24
	v_fmac_f32_e32 v37, v25, v25
	v_add_f32_e32 v36, v36, v37
	v_add_f32_e32 v35, v35, v36
	v_mul_f32_e32 v36, v26, v26
	v_fmac_f32_e32 v36, v27, v27
	v_mul_f32_e32 v37, v28, v28
	v_fmac_f32_e32 v37, v29, v29
	v_add_f32_e32 v36, v36, v37
	v_add_f32_e32 v35, v35, v36
	v_mul_f32_e32 v36, v30, v30
	v_fmac_f32_e32 v36, v31, v31
	v_mul_f32_e32 v37, v32, v32
	v_fmac_f32_e32 v37, v33, v33
	v_add_f32_e32 v36, v36, v37
	v_add_f32_e32 v35, v35, v36
	s_nop 1
	v_add_f32_dpp v35, v35, v35 quad_perm:[1,0,3,2] row_mask:0xf bank_mask:0xf
	s_nop 1
	v_add_f32_dpp v35, v35, v35 quad_perm:[2,3,0,1] row_mask:0xf bank_mask:0xf
	s_nop 1
	v_add_f32_dpp v35, v35, v35 row_half_mirror row_mask:0xf bank_mask:0xf
	s_nop 1
	v_add_f32_dpp v35, v35, v35 row_mirror row_mask:0xf bank_mask:0xf
	s_nop 1
	v_mov_b32_e32 v38, v35
	s_nop 1
	v_permlane16_swap_b32_e32 v38, v35
	s_nop 1
	v_add_f32_e32 v35, v38, v35
	v_mov_b32_e32 v38, v35
	s_nop 1
	v_permlane32_swap_b32_e32 v38, v35
	s_nop 1
	v_add_f32_e32 v35, v38, v35
	v_fmamk_f32 v35, v35, 0x3a800000, v137
	v_rsq_f32_e32 v35, v35
	v_mul_f32_e32 v34, 0x3a800000, v34
	s_nop 0
	v_mul_f32_e32 v18, v18, v35
	v_mul_f32_e32 v19, v19, v35
	v_mul_f32_e32 v20, v20, v35
	v_mul_f32_e32 v21, v21, v35
	v_mul_f32_e32 v22, v22, v35
	v_mul_f32_e32 v23, v23, v35
	v_mul_f32_e32 v24, v24, v35
	v_mul_f32_e32 v25, v25, v35
	v_mul_f32_e32 v26, v26, v35
	v_mul_f32_e32 v27, v27, v35
	v_mul_f32_e32 v28, v28, v35
	v_mul_f32_e32 v29, v29, v35
	v_mul_f32_e32 v30, v30, v35
	v_mul_f32_e32 v31, v31, v35
	v_mul_f32_e32 v32, v32, v35
	v_mul_f32_e32 v33, v33, v35
	v_fma_f32 v18, v64, v18, v80
	v_fma_f32 v19, v65, v19, v81
	v_fma_f32 v20, v66, v20, v82
	v_fma_f32 v21, v67, v21, v83
	v_fma_f32 v22, v68, v22, v84
	v_fma_f32 v23, v69, v23, v85
	v_fma_f32 v24, v70, v24, v86
	v_fma_f32 v25, v71, v25, v87
	v_fma_f32 v26, v72, v26, v88
	v_fma_f32 v27, v73, v27, v89
	v_fma_f32 v28, v74, v28, v90
	v_fma_f32 v29, v75, v29, v91
	v_fma_f32 v30, v76, v30, v92
	v_fma_f32 v31, v77, v31, v93
	v_fma_f32 v32, v78, v32, v94
	v_fma_f32 v33, v79, v33, v95
	s_add_i32 s30, s10, 8192
	s_cmp_eq_u32 s14, 1
	s_cbranch_scc1 .Lln3_last_4
	s_lshl_b32 s4, s30, 11
	s_add_u32 s26, s44, s4
	s_addc_u32 s27, s45, 0
	v_cvt_pk_bf16_f32 v40, v18, v19
	v_cvt_pk_bf16_f32 v41, v20, v21
	global_store_dwordx2 v62, v[40:41], s[26:27]
	v_cvt_pk_bf16_f32 v42, v22, v23
	v_cvt_pk_bf16_f32 v43, v24, v25
	global_store_dwordx2 v62, v[42:43], s[26:27] offset:512
	v_cvt_pk_bf16_f32 v44, v26, v27
	v_cvt_pk_bf16_f32 v45, v28, v29
	global_store_dwordx2 v62, v[44:45], s[26:27] offset:1024
	v_cvt_pk_bf16_f32 v46, v30, v31
	v_cvt_pk_bf16_f32 v47, v32, v33
	global_store_dwordx2 v62, v[46:47], s[26:27] offset:1536
	s_lshl_b32 s4, s30, 3
	s_add_u32 s26, s48, s4
	s_addc_u32 s27, s49, 0
	s_mov_b64 s[54:55], exec
	v_cmp_eq_u32_e32 vcc, 0, v60
	s_and_b64 exec, exec, vcc
	global_store_dwordx2 v63, v[34:35], s[26:27]
	s_mov_b64 exec, s[54:55]
	s_branch .Lln3_next_4

; DEVI unsigned pk_bf16(float lo, float hi) { const bf16x2n r = __builtin_convertvector((f32x2v){lo, hi}, bf16x2n); return __builtin_bit_cast(unsigned, r); }
; DEVI void phase_ln(const Params& p, int l, int which, bool last) {
;     ...
;     for (; row < T_; row += stride) {
;         f32x4 v[4];
; #pragma unroll
;         for (int i = 0; i < 4; ++i) v[i] = nx[i];
;         const int rn = row + stride < T_ ? row + stride : row;
; #pragma unroll
;         for (int i = 0; i < 4; ++i) nx[i] = *(const f32x4*)(hbuf + (size_t)rn * D_ + i * 256 + lane * 4);
;         float s = 0.f;
; #pragma unroll
;         for (int i = 0; i < 4; ++i) s += (v[i][0] + v[i][1]) + (v[i][2] + v[i][3]);
; #pragma unroll
;         for (int o = 32; o > 0; o >>= 1) s += __shfl_xor(s, o);
;         const float mu = s * (1.0f / 1024.0f);
;         float q = 0.f;
; #pragma unroll
;         for (int i = 0; i < 4; ++i) { const f32x4 d = v[i] - mu; q += (d[0] * d[0] + d[1] * d[1]) + (d[2] * d[2] + d[3] * d[3]); }
; #pragma unroll
;         for (int o = 32; o > 0; o >>= 1) q += __shfl_xor(q, o);
;         const float rstd = rsqrtf(q * (1.0f / 1024.0f) + 1e-5f);
; #pragma unroll
;         for (int i = 0; i < 4; ++i) {
;             const int c0 = i * 256 + lane * 4;
;             const f32x4 gg = *(const f32x4*)(g + c0), bb = *(const f32x4*)(b + c0);
;             const f32x4 o = (v[i] - mu) * rstd * gg + bb;
;             if (last) *(f32x4*)(dst + (size_t)row * D_ + c0) = o;
;             else { u32x2 pk; pk.x = pk_bf16(o[0], o[1]); pk.y = pk_bf16(o[2], o[3]); *(u32x2*)(hb + (size_t)row * D_ + c0) = pk; }
;         }
;         if (!last && lane == 0) ((f32x2v*)(p.ws + OFF_STATS))[row] = (f32x2v){mu, rstd};
;     }
.Lln3_next_4:
	s_nop 1
	s_add_i32 s4, s10, 14336
	s_lshl_b32 s4, s4, 12
	s_add_u32 s24, s42, s4
	s_addc_u32 s25, s43, 0
	global_load_dwordx4 v[18:21], v61, s[24:25]
	global_load_dwordx4 v[22:25], v61, s[24:25] offset:1024
	global_load_dwordx4 v[26:29], v61, s[24:25] offset:2048
	global_load_dwordx4 v[30:33], v61, s[24:25] offset:3072
	s_waitcnt vmcnt(16)
	v_add_f32_e32 v36, v96, v97
	v_add_f32_e32 v37, v98, v99
	v_add_f32_e32 v34, v36, v37
	v_add_f32_e32 v36, v100, v101
	v_add_f32_e32 v37, v102, v103
	v_add_f32_e32 v36, v36, v37
	v_add_f32_e32 v34, v34, v36
	v_add_f32_e32 v36, v104, v105
	v_add_f32_e32 v37, v106, v107
	v_add_f32_e32 v36, v36, v37
	v_add_f32_e32 v34, v34, v36
	v_add_f32_e32 v36, v108, v109
	v_add_f32_e32 v37, v110, v111
	v_add_f32_e32 v36, v36, v37
	v_add_f32_e32 v34, v34, v36
	s_nop 1
	v_add_f32_dpp v34, v34, v34 quad_perm:[1,0,3,2] row_mask:0xf bank_mask:0xf
	s_nop 1
	v_add_f32_dpp v34, v34, v34 quad_perm:[2,3,0,1] row_mask:0xf bank_mask:0xf
	s_nop 1
	v_add_f32_dpp v34, v34, v34 row_half_mirror row_mask:0xf bank_mask:0xf
	s_nop 1
	v_add_f32_dpp v34, v34, v34 row_mirror row_mask:0xf bank_mask:0xf
	s_nop 1
	v_mov_b32_e32 v38, v34
	s_nop 1
	v_permlane16_swap_b32_e32 v38, v34
	s_nop 1
	v_add_f32_e32 v34, v38, v34
	v_mov_b32_e32 v38, v34
	s_nop 1
	v_permlane32_swap_b32_e32 v38, v34
	s_nop 1
	v_add_f32_e32 v34, v38, v34
	v_fmac_f32_e32 v96, 0xba800000, v34
	v_fmac_f32_e32 v97, 0xba800000, v34
	v_fmac_f32_e32 v98, 0xba800000, v34
	v_fmac_f32_e32 v99, 0xba800000, v34
	v_fmac_f32_e32 v100, 0xba800000, v34
	v_fmac_f32_e32 v101, 0xba800000, v34
	v_fmac_f32_e32 v102, 0xba800000, v34
	v_fmac_f32_e32 v103, 0xba800000, v34
	v_fmac_f32_e32 v104, 0xba800000, v34
	v_fmac_f32_e32 v105, 0xba800000, v34
	v_fmac_f32_e32 v106, 0xba800000, v34
	v_fmac_f32_e32 v107, 0xba800000, v34
	v_fmac_f32_e32 v108, 0xba800000, v34
	v_fmac_f32_e32 v109, 0xba800000, v34
	v_fmac_f32_e32 v110, 0xba800000, v34
	v_fmac_f32_e32 v111, 0xba800000, v34
	v_mul_f32_e32 v36, v96, v96
	v_fmac_f32_e32 v36, v97, v97
	v_mul_f32_e32 v37, v98, v98
	v_fmac_f32_e32 v37, v99, v99
	v_add_f32_e32 v35, v36, v37
	v_mul_f32_e32 v36, v100, v100
	v_fmac_f32_e32 v36, v101, v101
	v_mul_f32_e32 v37, v102, v102
	v_fmac_f32_e32 v37, v103, v103
	v_add_f32_e32 v36, v36, v37
	v_add_f32_e32 v35, v35, v36
	v_mul_f32_e32 v36, v104, v104
	v_fmac_f32_e32 v36, v105, v105
	v_mul_f32_e32 v37, v106, v106
	v_fmac_f32_e32 v37, v107, v107
	v_add_f32_e32 v36, v36, v37
	v_add_f32_e32 v35, v35, v36
	v_mul_f32_e32 v36, v108, v108
	v_fmac_f32_e32 v36, v109, v109
	v_mul_f32_e32 v37, v110, v110
	v_fmac_f32_e32 v37, v111, v111
	v_add_f32_e32 v36, v36, v37
	v_add_f32_e32 v35, v35, v36
	s_nop 1
	v_add_f32_dpp v35, v35, v35 quad_perm:[1,0,3,2] row_mask:0xf bank_mask:0xf
	s_nop 1
	v_add_f32_dpp v35, v35, v35 quad_perm:[2,3,0,1] row_mask:0xf bank_mask:0xf
	s_nop 1
	v_add_f32_dpp v35, v35, v35 row_half_mirror row_mask:0xf bank_mask:0xf
	s_nop 1
	v_add_f32_dpp v35, v35, v35 row_mirror row_mask:0xf bank_mask:0xf
	s_nop 1
	v_mov_b32_e32 v38, v35
	s_nop 1
	v_permlane16_swap_b32_e32 v38, v35
	s_nop 1
	v_add_f32_e32 v35, v38, v35
	v_mov_b32_e32 v38, v35
	s_nop 1
	v_permlane32_swap_b32_e32 v38, v35
	s_nop 1
	v_add_f32_e32 v35, v38, v35
	v_fmamk_f32 v35, v35, 0x3a800000, v137
	v_rsq_f32_e32 v35, v35
	v_mul_f32_e32 v34, 0x3a800000, v34
	s_nop 0
	v_mul_f32_e32 v96, v96, v35
	v_mul_f32_e32 v97, v97, v35
	v_mul_f32_e32 v98, v98, v35
	v_mul_f32_e32 v99, v99, v35
	v_mul_f32_e32 v100, v100, v35
	v_mul_f32_e32 v101, v101, v35
	v_mul_f32_e32 v102, v102, v35
	v_mul_f32_e32 v103, v103, v35
	v_mul_f32_e32 v104, v104, v35
	v_mul_f32_e32 v105, v105, v35
	v_mul_f32_e32 v106, v106, v35
	v_mul_f32_e32 v107, v107, v35
	v_mul_f32_e32 v108, v108, v35
	v_mul_f32_e32 v109, v109, v35
	v_mul_f32_e32 v110, v110, v35
	v_mul_f32_e32 v111, v111, v35
	v_fma_f32 v96, v64, v96, v80
	v_fma_f32 v97, v65, v97, v81
	v_fma_f32 v98, v66, v98, v82
	v_fma_f32 v99, v67, v99, v83
	v_fma_f32 v100, v68, v100, v84
	v_fma_f32 v101, v69, v101, v85
	v_fma_f32 v102, v70, v102, v86
	v_fma_f32 v103, v71, v103, v87
	v_fma_f32 v104, v72, v104, v88
	v_fma_f32 v105, v73, v105, v89
	v_fma_f32 v106, v74, v106, v90
	v_fma_f32 v107, v75, v107, v91
	v_fma_f32 v108, v76, v108, v92
	v_fma_f32 v109, v77, v109, v93
	v_fma_f32 v110, v78, v110, v94
	v_fma_f32 v111, v79, v111, v95
	s_add_i32 s30, s10, 10240
	s_cmp_eq_u32 s14, 1
	s_cbranch_scc1 .Lln3_last_5
	s_lshl_b32 s4, s30, 11
	s_add_u32 s26, s44, s4
	s_addc_u32 s27, s45, 0
	v_cvt_pk_bf16_f32 v40, v96, v97
	v_cvt_pk_bf16_f32 v41, v98, v99
	global_store_dwordx2 v62, v[40:41], s[26:27]
	v_cvt_pk_bf16_f32 v42, v100, v101
	v_cvt_pk_bf16_f32 v43, v102, v103
	global_store_dwordx2 v62, v[42:43], s[26:27] offset:512
	v_cvt_pk_bf16_f32 v44, v104, v105
	v_cvt_pk_bf16_f32 v45, v106, v107
	global_store_dwordx2 v62, v[44:45], s[26:27] offset:1024
	v_cvt_pk_bf16_f32 v46, v108, v109
	v_cvt_pk_bf16_f32 v47, v110, v111
	global_store_dwordx2 v62, v[46:47], s[26:27] offset:1536
	s_lshl_b32 s4, s30, 3
	s_add_u32 s26, s48, s4
	s_addc_u32 s27, s49, 0
	s_mov_b64 s[54:55], exec
	v_cmp_eq_u32_e32 vcc, 0, v60
	s_and_b64 exec, exec, vcc
	global_store_dwordx2 v63, v[34:35], s[26:27]
	s_mov_b64 exec, s[54:55]
	s_branch .Lln3_next_5

; DEVI unsigned pk_bf16(float lo, float hi) { const bf16x2n r = __builtin_convertvector((f32x2v){lo, hi}, bf16x2n); return __builtin_bit_cast(unsigned, r); }
; DEVI void phase_ln(const Params& p, int l, int which, bool last) {
;     ...
;     for (; row < T_; row += stride) {
;         f32x4 v[4];
; #pragma unroll
;         for (int i = 0; i < 4; ++i) v[i] = nx[i];
;         const int rn = row + stride < T_ ? row + stride : row;
; #pragma unroll
;         for (int i = 0; i < 4; ++i) nx[i] = *(const f32x4*)(hbuf + (size_t)rn * D_ + i * 256 + lane * 4);
;         float s = 0.f;
; #pragma unroll
;         for (int i = 0; i < 4; ++i) s += (v[i][0] + v[i][1]) + (v[i][2] + v[i][3]);
; #pragma unroll
;         for (int o = 32; o > 0; o >>= 1) s += __shfl_xor(s, o);
;         const float mu = s * (1.0f / 1024.0f);
;         float q = 0.f;
; #pragma unroll
;         for (int i = 0; i < 4; ++i) { const f32x4 d = v[i] - mu; q += (d[0] * d[0] + d[1] * d[1]) + (d[2] * d[2] + d[3] * d[3]); }
; #pragma unroll
;         for (int o = 32; o > 0; o >>= 1) q += __shfl_xor(q, o);
;         const float rstd = rsqrtf(q * (1.0f / 1024.0f) + 1e-5f);
; #pragma unroll
;         for (int i = 0; i < 4; ++i) {
;             const int c0 = i * 256 + lane * 4;
;             const f32x4 gg = *(const f32x4*)(g + c0), bb = *(const f32x4*)(b + c0);
;             const f32x4 o = (v[i] - mu) * rstd * gg + bb;
;             if (last) *(f32x4*)(dst + (size_t)row * D_ + c0) = o;
;             else { u32x2 pk; pk.x = pk_bf16(o[0], o[1]); pk.y = pk_bf16(o[2], o[3]); *(u32x2*)(hb + (size_t)row * D_ + c0) = pk; }
;         }
;         if (!last && lane == 0) ((f32x2v*)(p.ws + OFF_STATS))[row] = (f32x2v){mu, rstd};
;     }
.Lln3_next_5:
	s_waitcnt vmcnt(12)
	v_add_f32_e32 v36, v2, v3
	v_add_f32_e32 v37, v4, v5
	v_add_f32_e32 v34, v36, v37
	v_add_f32_e32 v36, v6, v7
	v_add_f32_e32 v37, v8, v9
	v_add_f32_e32 v36, v36, v37
	v_add_f32_e32 v34, v34, v36
	v_add_f32_e32 v36, v10, v11
	v_add_f32_e32 v37, v12, v13
	v_add_f32_e32 v36, v36, v37
	v_add_f32_e32 v34, v34, v36
	v_add_f32_e32 v36, v14, v15
	v_add_f32_e32 v37, v16, v17
	v_add_f32_e32 v36, v36, v37
	v_add_f32_e32 v34, v34, v36
	s_nop 1
	v_add_f32_dpp v34, v34, v34 quad_perm:[1,0,3,2] row_mask:0xf bank_mask:0xf
	s_nop 1
	v_add_f32_dpp v34, v34, v34 quad_perm:[2,3,0,1] row_mask:0xf bank_mask:0xf
	s_nop 1
	v_add_f32_dpp v34, v34, v34 row_half_mirror row_mask:0xf bank_mask:0xf
	s_nop 1
	v_add_f32_dpp v34, v34, v34 row_mirror row_mask:0xf bank_mask:0xf
	s_nop 1
	v_mov_b32_e32 v38, v34
	s_nop 1
	v_permlane16_swap_b32_e32 v38, v34
	s_nop 1
	v_add_f32_e32 v34, v38, v34
	v_mov_b32_e32 v38, v34
	s_nop 1
	v_permlane32_swap_b32_e32 v38, v34
	s_nop 1
	v_add_f32_e32 v34, v38, v34
	v_fmac_f32_e32 v2, 0xba800000, v34
	v_fmac_f32_e32 v3, 0xba800000, v34
	v_fmac_f32_e32 v4, 0xba800000, v34
	v_fmac_f32_e32 v5, 0xba800000, v34
	v_fmac_f32_e32 v6, 0xba800000, v34
	v_fmac_f32_e32 v7, 0xba800000, v34
	v_fmac_f32_e32 v8, 0xba800000, v34
	v_fmac_f32_e32 v9, 0xba800000, v34
	v_fmac_f32_e32 v10, 0xba800000, v34
	v_fmac_f32_e32 v11, 0xba800000, v34
	v_fmac_f32_e32 v12, 0xba800000, v34
	v_fmac_f32_e32 v13, 0xba800000, v34
	v_fmac_f32_e32 v14, 0xba800000, v34
	v_fmac_f32_e32 v15, 0xba800000, v34
	v_fmac_f32_e32 v16, 0xba800000, v34
	v_fmac_f32_e32 v17, 0xba800000, v34
	v_mul_f32_e32 v36, v2, v2
	v_fmac_f32_e32 v36, v3, v3
	v_mul_f32_e32 v37, v4, v4
	v_fmac_f32_e32 v37, v5, v5
	v_add_f32_e32 v35, v36, v37
	v_mul_f32_e32 v36, v6, v6
	v_fmac_f32_e32 v36, v7, v7
	v_mul_f32_e32 v37, v8, v8
	v_fmac_f32_e32 v37, v9, v9
	v_add_f32_e32 v36, v36, v37
	v_add_f32_e32 v35, v35, v36
	v_mul_f32_e32 v36, v10, v10
	v_fmac_f32_e32 v36, v11, v11
	v_mul_f32_e32 v37, v12, v12
	v_fmac_f32_e32 v37, v13, v13
	v_add_f32_e32 v36, v36, v37
	v_add_f32_e32 v35, v35, v36
	v_mul_f32_e32 v36, v14, v14
	v_fmac_f32_e32 v36, v15, v15
	v_mul_f32_e32 v37, v16, v16
	v_fmac_f32_e32 v37, v17, v17
	v_add_f32_e32 v36, v36, v37
	v_add_f32_e32 v35, v35, v36
	s_nop 1
	v_add_f32_dpp v35, v35, v35 quad_perm:[1,0,3,2] row_mask:0xf bank_mask:0xf
	s_nop 1
	v_add_f32_dpp v35, v35, v35 quad_perm:[2,3,0,1] row_mask:0xf bank_mask:0xf
	s_nop 1
	v_add_f32_dpp v35, v35, v35 row_half_mirror row_mask:0xf bank_mask:0xf
	s_nop 1
	v_add_f32_dpp v35, v35, v35 row_mirror row_mask:0xf bank_mask:0xf
	s_nop 1
	v_mov_b32_e32 v38, v35
	s_nop 1
	v_permlane16_swap_b32_e32 v38, v35
	s_nop 1
	v_add_f32_e32 v35, v38, v35
	v_mov_b32_e32 v38, v35
	s_nop 1
	v_permlane32_swap_b32_e32 v38, v35
	s_nop 1
	v_add_f32_e32 v35, v38, v35
	v_fmamk_f32 v35, v35, 0x3a800000, v137
	v_rsq_f32_e32 v35, v35
	v_mul_f32_e32 v34, 0x3a800000, v34
	s_nop 0
	v_mul_f32_e32 v2, v2, v35
	v_mul_f32_e32 v3, v3, v35
	v_mul_f32_e32 v4, v4, v35
	v_mul_f32_e32 v5, v5, v35
	v_mul_f32_e32 v6, v6, v35
	v_mul_f32_e32 v7, v7, v35
	v_mul_f32_e32 v8, v8, v35
	v_mul_f32_e32 v9, v9, v35
	v_mul_f32_e32 v10, v10, v35
	v_mul_f32_e32 v11, v11, v35
	v_mul_f32_e32 v12, v12, v35
	v_mul_f32_e32 v13, v13, v35
	v_mul_f32_e32 v14, v14, v35
	v_mul_f32_e32 v15, v15, v35
	v_mul_f32_e32 v16, v16, v35
	v_mul_f32_e32 v17, v17, v35
	v_fma_f32 v2, v64, v2, v80
	v_fma_f32 v3, v65, v3, v81
	v_fma_f32 v4, v66, v4, v82
	v_fma_f32 v5, v67, v5, v83
	v_fma_f32 v6, v68, v6, v84
	v_fma_f32 v7, v69, v7, v85
	v_fma_f32 v8, v70, v8, v86
	v_fma_f32 v9, v71, v9, v87
	v_fma_f32 v10, v72, v10, v88
	v_fma_f32 v11, v73, v11, v89
	v_fma_f32 v12, v74, v12, v90
	v_fma_f32 v13, v75, v13, v91
	v_fma_f32 v14, v76, v14, v92
	v_fma_f32 v15, v77, v15, v93
	v_fma_f32 v16, v78, v16, v94
	v_fma_f32 v17, v79, v17, v95
	s_add_i32 s30, s10, 12288
	s_cmp_eq_u32 s14, 1
	s_cbranch_scc1 .Lln3_last_6
	s_lshl_b32 s4, s30, 11
	s_add_u32 s26, s44, s4
	s_addc_u32 s27, s45, 0
	v_cvt_pk_bf16_f32 v40, v2, v3
	v_cvt_pk_bf16_f32 v41, v4, v5
	global_store_dwordx2 v62, v[40:41], s[26:27]
	v_cvt_pk_bf16_f32 v42, v6, v7
	v_cvt_pk_bf16_f32 v43, v8, v9
	global_store_dwordx2 v62, v[42:43], s[26:27] offset:512
	v_cvt_pk_bf16_f32 v44, v10, v11
	v_cvt_pk_bf16_f32 v45, v12, v13
	global_store_dwordx2 v62, v[44:45], s[26:27] offset:1024
	v_cvt_pk_bf16_f32 v46, v14, v15
	v_cvt_pk_bf16_f32 v47, v16, v17
	global_store_dwordx2 v62, v[46:47], s[26:27] offset:1536
	s_lshl_b32 s4, s30, 3
	s_add_u32 s26, s48, s4
	s_addc_u32 s27, s49, 0
	s_mov_b64 s[54:55], exec
	v_cmp_eq_u32_e32 vcc, 0, v60
	s_and_b64 exec, exec, vcc
	global_store_dwordx2 v63, v[34:35], s[26:27]
	s_mov_b64 exec, s[54:55]
	s_branch .Lln3_next_6

; DEVI unsigned pk_bf16(float lo, float hi) { const bf16x2n r = __builtin_convertvector((f32x2v){lo, hi}, bf16x2n); return __builtin_bit_cast(unsigned, r); }
; DEVI void phase_ln(const Params& p, int l, int which, bool last) {
;     ...
;     for (; row < T_; row += stride) {
;         f32x4 v[4];
; #pragma unroll
;         for (int i = 0; i < 4; ++i) v[i] = nx[i];
;         const int rn = row + stride < T_ ? row + stride : row;
; #pragma unroll
;         for (int i = 0; i < 4; ++i) nx[i] = *(const f32x4*)(hbuf + (size_t)rn * D_ + i * 256 + lane * 4);
;         float s = 0.f;
; #pragma unroll
;         for (int i = 0; i < 4; ++i) s += (v[i][0] + v[i][1]) + (v[i][2] + v[i][3]);
; #pragma unroll
;         for (int o = 32; o > 0; o >>= 1) s += __shfl_xor(s, o);
;         const float mu = s * (1.0f / 1024.0f);
;         float q = 0.f;
; #pragma unroll
;         for (int i = 0; i < 4; ++i) { const f32x4 d = v[i] - mu; q += (d[0] * d[0] + d[1] * d[1]) + (d[2] * d[2] + d[3] * d[3]); }
; #pragma unroll
;         for (int o = 32; o > 0; o >>= 1) q += __shfl_xor(q, o);
;         const float rstd = rsqrtf(q * (1.0f / 1024.0f) + 1e-5f);
; #pragma unroll
;         for (int i = 0; i < 4; ++i) {
;             const int c0 = i * 256 + lane * 4;
;             const f32x4 gg = *(const f32x4*)(g + c0), bb = *(const f32x4*)(b + c0);
;             const f32x4 o = (v[i] - mu) * rstd * gg + bb;
;             if (last) *(f32x4*)(dst + (size_t)row * D_ + c0) = o;
;             else { u32x2 pk; pk.x = pk_bf16(o[0], o[1]); pk.y = pk_bf16(o[2], o[3]); *(u32x2*)(hb + (size_t)row * D_ + c0) = pk; }
;         }
;         if (!last && lane == 0) ((f32x2v*)(p.ws + OFF_STATS))[row] = (f32x2v){mu, rstd};
;     }
.Lln3_next_6:
	s_waitcnt vmcnt(8)
	v_add_f32_e32 v36, v18, v19
	v_add_f32_e32 v37, v20, v21
	v_add_f32_e32 v34, v36, v37
	v_add_f32_e32 v36, v22, v23
	v_add_f32_e32 v37, v24, v25
	v_add_f32_e32 v36, v36, v37
	v_add_f32_e32 v34, v34, v36
	v_add_f32_e32 v36, v26, v27
	v_add_f32_e32 v37, v28, v29
	v_add_f32_e32 v36, v36, v37
	v_add_f32_e32 v34, v34, v36
	v_add_f32_e32 v36, v30, v31
	v_add_f32_e32 v37, v32, v33
	v_add_f32_e32 v36, v36, v37
	v_add_f32_e32 v34, v34, v36
	s_nop 1
	v_add_f32_dpp v34, v34, v34 quad_perm:[1,0,3,2] row_mask:0xf bank_mask:0xf
	s_nop 1
	v_add_f32_dpp v34, v34, v34 quad_perm:[2,3,0,1] row_mask:0xf bank_mask:0xf
	s_nop 1
	v_add_f32_dpp v34, v34, v34 row_half_mirror row_mask:0xf bank_mask:0xf
	s_nop 1
	v_add_f32_dpp v34, v34, v34 row_mirror row_mask:0xf bank_mask:0xf
	s_nop 1
	v_mov_b32_e32 v38, v34
	s_nop 1
	v_permlane16_swap_b32_e32 v38, v34
	s_nop 1
	v_add_f32_e32 v34, v38, v34
	v_mov_b32_e32 v38, v34
	s_nop 1
	v_permlane32_swap_b32_e32 v38, v34
	s_nop 1
	v_add_f32_e32 v34, v38, v34
	v_fmac_f32_e32 v18, 0xba800000, v34
	v_fmac_f32_e32 v19, 0xba800000, v34
	v_fmac_f32_e32 v20, 0xba800000, v34
	v_fmac_f32_e32 v21, 0xba800000, v34
	v_fmac_f32_e32 v22, 0xba800000, v34
	v_fmac_f32_e32 v23, 0xba800000, v34
	v_fmac_f32_e32 v24, 0xba800000, v34
	v_fmac_f32_e32 v25, 0xba800000, v34
	v_fmac_f32_e32 v26, 0xba800000, v34
	v_fmac_f32_e32 v27, 0xba800000, v34
	v_fmac_f32_e32 v28, 0xba800000, v34
	v_fmac_f32_e32 v29, 0xba800000, v34
	v_fmac_f32_e32 v30, 0xba800000, v34
	v_fmac_f32_e32 v31, 0xba800000, v34
	v_fmac_f32_e32 v32, 0xba800000, v34
	v_fmac_f32_e32 v33, 0xba800000, v34
	v_mul_f32_e32 v36, v18, v18
	v_fmac_f32_e32 v36, v19, v19
	v_mul_f32_e32 v37, v20, v20
	v_fmac_f32_e32 v37, v21, v21
	v_add_f32_e32 v35, v36, v37
	v_mul_f32_e32 v36, v22, v22
	v_fmac_f32_e32 v36, v23, v23
	v_mul_f32_e32 v37, v24, v24
	v_fmac_f32_e32 v37, v25, v25
	v_add_f32_e32 v36, v36, v37
	v_add_f32_e32 v35, v35, v36
	v_mul_f32_e32 v36, v26, v26
	v_fmac_f32_e32 v36, v27, v27
	v_mul_f32_e32 v37, v28, v28
	v_fmac_f32_e32 v37, v29, v29
	v_add_f32_e32 v36, v36, v37
	v_add_f32_e32 v35, v35, v36
	v_mul_f32_e32 v36, v30, v30
	v_fmac_f32_e32 v36, v31, v31
	v_mul_f32_e32 v37, v32, v32
	v_fmac_f32_e32 v37, v33, v33
	v_add_f32_e32 v36, v36, v37
	v_add_f32_e32 v35, v35, v36
	s_nop 1
	v_add_f32_dpp v35, v35, v35 quad_perm:[1,0,3,2] row_mask:0xf bank_mask:0xf
	s_nop 1
	v_add_f32_dpp v35, v35, v35 quad_perm:[2,3,0,1] row_mask:0xf bank_mask:0xf
	s_nop 1
	v_add_f32_dpp v35, v35, v35 row_half_mirror row_mask:0xf bank_mask:0xf
	s_nop 1
	v_add_f32_dpp v35, v35, v35 row_mirror row_mask:0xf bank_mask:0xf
	s_nop 1
	v_mov_b32_e32 v38, v35
	s_nop 1
	v_permlane16_swap_b32_e32 v38, v35
	s_nop 1
	v_add_f32_e32 v35, v38, v35
	v_mov_b32_e32 v38, v35
	s_nop 1
	v_permlane32_swap_b32_e32 v38, v35
	s_nop 1
	v_add_f32_e32 v35, v38, v35
	v_fmamk_f32 v35, v35, 0x3a800000, v137
	v_rsq_f32_e32 v35, v35
	v_mul_f32_e32 v34, 0x3a800000, v34
	s_nop 0
	v_mul_f32_e32 v18, v18, v35
	v_mul_f32_e32 v19, v19, v35
	v_mul_f32_e32 v20, v20, v35
	v_mul_f32_e32 v21, v21, v35
	v_mul_f32_e32 v22, v22, v35
	v_mul_f32_e32 v23, v23, v35
	v_mul_f32_e32 v24, v24, v35
	v_mul_f32_e32 v25, v25, v35
	v_mul_f32_e32 v26, v26, v35
	v_mul_f32_e32 v27, v27, v35
	v_mul_f32_e32 v28, v28, v35
	v_mul_f32_e32 v29, v29, v35
	v_mul_f32_e32 v30, v30, v35
	v_mul_f32_e32 v31, v31, v35
	v_mul_f32_e32 v32, v32, v35
	v_mul_f32_e32 v33, v33, v35
	v_fma_f32 v18, v64, v18, v80
	v_fma_f32 v19, v65, v19, v81
	v_fma_f32 v20, v66, v20, v82
	v_fma_f32 v21, v67, v21, v83
	v_fma_f32 v22, v68, v22, v84
	v_fma_f32 v23, v69, v23, v85
	v_fma_f32 v24, v70, v24, v86
	v_fma_f32 v25, v71, v25, v87
	v_fma_f32 v26, v72, v26, v88
	v_fma_f32 v27, v73, v27, v89
	v_fma_f32 v28, v74, v28, v90
	v_fma_f32 v29, v75, v29, v91
	v_fma_f32 v30, v76, v30, v92
	v_fma_f32 v31, v77, v31, v93
	v_fma_f32 v32, v78, v32, v94
	v_fma_f32 v33, v79, v33, v95
	s_add_i32 s30, s10, 14336
	s_cmp_eq_u32 s14, 1
	s_cbranch_scc1 .Lln3_last_7
	s_lshl_b32 s4, s30, 11
	s_add_u32 s26, s44, s4
	s_addc_u32 s27, s45, 0
	v_cvt_pk_bf16_f32 v40, v18, v19
	v_cvt_pk_bf16_f32 v41, v20, v21
	global_store_dwordx2 v62, v[40:41], s[26:27]
	v_cvt_pk_bf16_f32 v42, v22, v23
	v_cvt_pk_bf16_f32 v43, v24, v25
	global_store_dwordx2 v62, v[42:43], s[26:27] offset:512
	v_cvt_pk_bf16_f32 v44, v26, v27
	v_cvt_pk_bf16_f32 v45, v28, v29
	global_store_dwordx2 v62, v[44:45], s[26:27] offset:1024
	v_cvt_pk_bf16_f32 v46, v30, v31
	v_cvt_pk_bf16_f32 v47, v32, v33
	global_store_dwordx2 v62, v[46:47], s[26:27] offset:1536
	s_lshl_b32 s4, s30, 3
	s_add_u32 s26, s48, s4
	s_addc_u32 s27, s49, 0
	s_mov_b64 s[54:55], exec
	v_cmp_eq_u32_e32 vcc, 0, v60
	s_and_b64 exec, exec, vcc
	global_store_dwordx2 v63, v[34:35], s[26:27]
	s_mov_b64 exec, s[54:55]
	s_branch .Lln3_next_7

; DEVI void phase_ln(const Params& p, int l, int which, bool last) {
;     ...
;     int row = blockIdx.x * 4 + wave;
;     f32x4 nx[4];
;     if (row < T_) {
; #pragma unroll
;         for (int i = 0; i < 4; ++i) nx[i] = *(const f32x4*)(hbuf + (size_t)row * D_ + i * 256 + lane * 4);
;     }
;     for (; row < T_; row += stride) {
;         f32x4 v[4];
; #pragma unroll
;         for (int i = 0; i < 4; ++i) v[i] = nx[i];
;         const int rn = row + stride < T_ ? row + stride : row;
; #pragma unroll
;         for (int i = 0; i < 4; ++i) nx[i] = *(const f32x4*)(hbuf + (size_t)rn * D_ + i * 256 + lane * 4);
.Lln_generic:
	s_cmpk_lt_i32 s10, 0x4000
	s_cbranch_scc0 .Lln_done
	s_lshl_b32 s4, s10, 12
	s_add_u32 s24, s42, s4
	s_addc_u32 s25, s43, 0
	global_load_dwordx4 v[18:21], v61, s[24:25]
	global_load_dwordx4 v[22:25], v61, s[24:25] offset:1024
	global_load_dwordx4 v[26:29], v61, s[24:25] offset:2048
	global_load_dwordx4 v[30:33], v61, s[24:25] offset:3072
